# p3warm: LoRA blocks touch the K/V GEMM operands (WK|WV, MN) once at P3 start so the latency-bound K/V blocks find them in the memory-side cache; on p3scanbal
# baseline (speedup 1.0000x reference)
.LBB0_530:
	s_and_b64 vcc, exec, s[0:1]
	s_cbranch_vccz .LBB0_583
	s_cmp_gt_i32 s69, 31
	s_mov_b64 s[0:1], -1
	s_cbranch_scc0 .LBB0_562
	s_cmp_gt_u32 s69, 63
	s_cbranch_scc0 .LBB0_554
	s_sub_i32 s98, s69, 64
	s_lshl_b32 s98, s98, 13
	v_lshlrev_b32_e32 v243, 4, v170
	v_add_u32_e32 v243, s98, v243
	s_add_u32 s100, s66, 0x2800000
	s_addc_u32 s101, s67, 0
	global_load_dword v236, v243, s[100:101]
	s_add_u32 s100, s100, 0x180000
	s_addc_u32 s101, s101, 0
	global_load_dword v237, v243, s[100:101]
	s_add_u32 s100, s100, 0x180000
	s_addc_u32 s101, s101, 0
	global_load_dword v238, v243, s[100:101]
	s_add_u32 s100, s100, 0x180000
	s_addc_u32 s101, s101, 0
	global_load_dword v239, v243, s[100:101]
	s_add_u32 s100, s100, 0x180000
	s_addc_u32 s101, s101, 0
	global_load_dword v240, v243, s[100:101]
	s_add_u32 s100, s100, 0x180000
	s_addc_u32 s101, s101, 0
	global_load_dword v241, v243, s[100:101]
	s_add_u32 s100, s100, 0x180000
	s_addc_u32 s101, s101, 0
	global_load_dword v242, v243, s[100:101]
	s_add_u32 s100, s100, 0x180000
	s_addc_u32 s101, s101, 0
	global_load_dword v236, v243, s[100:101]
	s_add_u32 s100, s100, 0x180000
	s_addc_u32 s101, s101, 0
	global_load_dword v237, v243, s[100:101]
	s_add_u32 s100, s100, 0x180000
	s_addc_u32 s101, s101, 0
	global_load_dword v238, v243, s[100:101]
	s_add_u32 s100, s100, 0x180000
	s_addc_u32 s101, s101, 0
	global_load_dword v239, v243, s[100:101]
	s_add_u32 s100, s100, 0x180000
	s_addc_u32 s101, s101, 0
	s_add_u32 s100, s66, 0x8400000
	s_addc_u32 s101, s67, 0
	global_load_dword v236, v243, s[100:101]
	s_add_u32 s100, s100, 0x180000
	s_addc_u32 s101, s101, 0
	global_load_dword v237, v243, s[100:101]
	s_add_u32 s100, s100, 0x180000
	s_addc_u32 s101, s101, 0
	global_load_dword v238, v243, s[100:101]
	s_sub_i32 s36, s69, 64
	s_cmpk_gt_u32 s36, 0x2ff
	v_readfirstlane_b32 s37, v170
	s_cbranch_scc1 .LBB0_553
	v_lshrrev_b32_e32 v0, 5, v170
	v_lshrrev_b32_e32 v2, 1, v170
	v_and_b32_e32 v0, 4, v0
	v_bfe_u32 v1, v170, 2, 2
	v_and_b32_e32 v11, 24, v2
	v_or3_b32 v0, v0, v1, v11
	v_lshlrev_b32_e32 v1, 4, v170
	v_add_u32_e32 v8, 0x2000, v1
	v_lshrrev_b32_e32 v2, 7, v8
	s_movk_i32 s0, 0xe0
	v_and_b32_e32 v4, 32, v170
	v_and_or_b32 v3, v2, s0, v0
	v_bitop3_b32 v9, v1, v4, 48 bitop3:0x6c
	v_and_b32_e32 v10, 64, v170
	v_bfe_u32 v12, v170, 2, 4
	s_movk_i32 s0, 0xf0
	v_or_b32_e32 v1, v9, v10
	v_and_or_b32 v2, v2, s0, v12
	v_lshl_or_b32 v146, v2, 10, v1
	v_lshrrev_b32_e32 v2, 3, v170
	s_movk_i32 s0, 0x60
	s_add_u32 s40, s66, 0x8000000
	v_and_or_b32 v0, v2, s0, v0
	s_movk_i32 s0, 0x70
	s_addc_u32 s41, s67, 0
	v_lshl_or_b32 v148, v0, 10, v1
	v_and_or_b32 v0, v2, s0, v12
	s_and_b32 s0, s69, 7
	s_lshr_b32 s1, s36, 3
	s_mulk_i32 s0, 0x60
	s_add_i32 s0, s0, s1
	s_mul_i32 s1, s0, 0xaaab
	s_lshr_b32 s1, s1, 21
	s_lshl_b32 s12, s1, 2
	s_mul_i32 s1, s1, 48
	s_sub_i32 s0, s0, s1
	s_and_b32 s1, s0, 3
	s_lshr_b32 s2, s37, 6
	s_or_b32 s12, s12, s1
	s_bfe_u32 s13, s0, 0x60002
	s_lshr_b32 s3, s37, 8
	s_lshl_b32 s42, s2, 10
	s_lshl_b32 s0, s12, 18
	s_lshl_b32 s1, s13, 18
	s_lshr_b32 s98, s13, 2
	s_add_i32 s99, s98, 1
	s_mul_i32 s98, s98, s99
	s_lshl_b32 s98, s98, 6
	s_add_i32 s0, s0, s98
	s_add_i32 s1, s1, s98
	s_add_u32 s30, s40, s1
	s_addc_u32 s31, s41, 0
	s_add_i32 s43, s42, 0
	s_add_i32 m0, s43, 0x10000
	v_lshl_or_b32 v144, v3, 10, v1
	global_load_lds_dwordx4 v148, s[30:31]
	s_add_i32 m0, s43, 0x12000
	s_add_u32 s0, s38, s0
	v_lshl_or_b32 v150, v0, 10, v1
	global_load_lds_dwordx4 v144, s[30:31]
	s_addc_u32 s1, s39, 0
	s_mov_b32 m0, s43
	s_add_i32 s44, s43, 0x2000
	global_load_lds_dwordx4 v150, s[0:1]
	s_mov_b32 m0, s44
	s_add_u32 s14, s30, 0x20000
	global_load_lds_dwordx4 v146, s[0:1]
	s_addc_u32 s15, s31, 0
	s_add_i32 m0, s43, 0x14000
	v_mov_b32_e32 v153, 0
	global_load_lds_dwordx4 v148, s[14:15]
	s_add_i32 m0, s43, 0x16000
	v_mov_b32_e32 v149, v153
	global_load_lds_dwordx4 v144, s[14:15]
	s_add_u32 s14, s0, 0x20000
	s_addc_u32 s15, s1, 0
	s_add_i32 s45, s43, 0x4000
	s_mov_b32 m0, s45
	s_add_i32 s46, s43, 0x6000
	global_load_lds_dwordx4 v150, s[14:15]
	s_mov_b32 m0, s46
	v_mov_b32_e32 v145, v153
	global_load_lds_dwordx4 v146, s[14:15]
	v_mov_b32_e32 v151, v153
	v_mov_b32_e32 v147, v153
	s_mov_b32 s47, 0
	v_lshl_add_u64 v[6:7], s[30:31], 0, v[148:149]
	v_lshl_add_u64 v[4:5], s[30:31], 0, v[144:145]
	v_lshl_add_u64 v[2:3], s[0:1], 0, v[150:151]
	s_cmp_lg_u32 s3, 1
	v_lshl_add_u64 v[0:1], s[0:1], 0, v[146:147]
	s_cbranch_scc1 .LBB0_536
	s_barrier
